# P0-SPLIT2: 58% of the weight conversion deferred from phase 0 into tail-round idle workgroups of phases 1, 3, 9 and 11 (virtual-index unit map), on top of v062
# speedup vs baseline: 1.0206x; 1.0120x over previous
.LBB0_282:
	s_or_b64 exec, exec, s[22:23]
	v_readlane_b32 s0, v249, 12
	v_readlane_b32 s1, v249, 13
	s_andn2_b64 vcc, exec, s[0:1]
	s_cbranch_vccnz .LBB0_391
	s_mov_b32 s100, s98
	s_movk_i32 s101, 0x209f
	s_mov_b32 s83, 0
	s_cmpk_lg_u32 s98, 0x100
	s_cbranch_scc1 .Lp0_pre
	s_movk_i32 s101, 0x129f
.Lp0_pre:
	s_sub_i32 s82, s69, s100
	v_lshlrev_b32_e32 v6, 4, v2
	v_and_b32_e32 v6, 48, v6
	v_ashrrev_i32_e32 v1, 8, v2
	s_movk_i32 s0, 0x4100
	v_lshlrev_b32_e32 v4, 2, v2
	s_waitcnt lgkmcnt(0)
	v_mul_u32_u24_e32 v11, 0x41, v6
	v_and_b32_e32 v5, 63, v2
	v_ashrrev_i32_e32 v7, 6, v2
	v_mad_i32_i24 v3, v1, s0, 0
	v_bfe_u32 v10, v2, 4, 4
	v_and_b32_e32 v4, 60, v4
	v_bfe_u32 v43, v2, 2, 6
	v_lshlrev_b32_e32 v11, 2, v11
	v_and_b32_e32 v2, 0xfc, v2
	v_readlane_b32 s40, v250, 2
	v_lshl_add_u32 v8, v4, 2, v3
	v_add3_u32 v44, v3, v11, v2
	v_add3_u32 v45, v3, v2, v11
	v_lshlrev_b32_e32 v2, 4, v5
	v_mov_b32_e32 v3, v0
	v_readlane_b32 s41, v250, 3
	v_readlane_b32 s42, v250, 4
	v_readlane_b32 s43, v250, 5
	v_readlane_b32 s0, v243, 3
	v_lshl_add_u64 v[14:15], s[40:41], 0, v[2:3]
	v_lshl_add_u64 v[12:13], s[42:43], 0, v[2:3]
	v_lshlrev_b32_e32 v2, 3, v5
	v_readlane_b32 s1, v243, 4
	v_mul_u32_u24_e32 v9, 0x104, v10
	v_cmp_eq_u32_e64 s[38:39], 0, v5
	v_lshl_add_u64 v[16:17], s[0:1], 0, v[2:3]
	v_readlane_b32 s0, v249, 14
	v_readlane_b32 s1, v249, 15
	v_or_b32_e32 v39, 16, v10
	v_or_b32_e32 v41, 32, v10
	v_lshl_add_u64 v[18:19], s[0:1], 0, v[2:3]
	v_readlane_b32 s0, v248, 59
	v_or_b32_e32 v42, 48, v10
	v_mov_b32_e32 v11, v0
	v_add_u32_e32 v20, s0, v7
	v_readlane_b32 s0, v248, 60
	v_lshlrev_b32_e32 v22, 2, v4
	v_lshlrev_b32_e32 v24, 1, v6
	v_add_u32_e32 v46, s0, v1
	v_add_u32_e32 v47, v8, v9
	s_mov_b32 s2, s69
	s_mov_b32 s16, 0xb00000
	s_mov_b32 s21, 0x580000
	v_readlane_b32 s44, v250, 6
	v_readlane_b32 s45, v250, 7
	v_readlane_b32 s46, v250, 8
	v_readlane_b32 s47, v250, 9
	v_readlane_b32 s48, v250, 10
	v_readlane_b32 s49, v250, 11
	v_readlane_b32 s50, v250, 12
	v_readlane_b32 s51, v250, 13
	v_readlane_b32 s52, v250, 14
	v_readlane_b32 s53, v250, 15
	v_readlane_b32 s54, v250, 16
	v_readlane_b32 s55, v250, 17
	s_branch .LBB0_286

.LBB0_286:
	s_add_i32 s82, s82, s100
	s_cmp_gt_i32 s82, s101
	s_cbranch_scc1 .LBB0_391
	s_mov_b32 s2, s82
	s_cmp_eq_u32 s83, 0
	s_cbranch_scc0 .Lp0m_sub
	s_cmpk_lg_u32 s98, 0x100
	s_cbranch_scc1 .Lp0m_done
	s_cmpk_lt_i32 s82, 768
	s_cbranch_scc1 .Lp0m_done
	s_addk_i32 s2, 512
	s_cmpk_lt_i32 s82, 1280
	s_cbranch_scc1 .Lp0m_done
	s_addk_i32 s2, 2304
	s_cmpk_lt_i32 s82, 1536
	s_cbranch_scc1 .Lp0m_done
	s_addk_i32 s2, 128
	s_cmpk_lt_i32 s82, 2176
	s_cbranch_scc1 .Lp0m_done
	s_addk_i32 s2, 128
	s_cmpk_lt_i32 s82, 2592
	s_cbranch_scc1 .Lp0m_done
	s_addk_i32 s2, 512
	s_branch .Lp0m_done
.Lp0m_sub:
	s_cmp_eq_u32 s83, 1
	s_cbranch_scc1 .Lp0m_1
	s_cmp_eq_u32 s83, 3
	s_cbranch_scc1 .Lp0m_3
	s_cmp_eq_u32 s83, 9
	s_cbranch_scc1 .Lp0m_9
	s_branch .Lp0m_11
.Lp0m_1:
	s_addk_i32 s2, 1792
	s_branch .Lp0m_done
.Lp0m_3:
	s_addk_i32 s2, 2432
	s_cmpk_lt_i32 s82, 384
	s_cbranch_scc1 .Lp0m_done
	s_addk_i32 s2, 704
	s_cmpk_lt_i32 s82, 736
	s_cbranch_scc1 .Lp0m_done
	s_addk_i32 s2, -3104
	s_cmpk_lt_i32 s82, 1248
	s_cbranch_scc1 .Lp0m_done
	s_addk_i32 s2, 4384
	s_branch .Lp0m_done
.Lp0m_9:
	s_addk_i32 s2, 2816
	s_branch .Lp0m_done
.Lp0m_11:
	s_addk_i32 s2, 3872
	s_cmpk_lt_i32 s82, 224
	s_cbranch_scc1 .Lp0m_done
	s_addk_i32 s2, 256
	s_cmpk_lt_i32 s82, 352
	s_cbranch_scc1 .Lp0m_done
	s_addk_i32 s2, 640
	s_branch .Lp0m_done
.Lp0m_done:
	v_lshl_add_u32 v46, s2, 1, v1
	v_lshrrev_b32_e32 v20, 6, v220
	v_lshl_add_u32 v20, s2, 3, v20
	v_add_u32_e32 v20, 0xfffeff00, v20

.LBB0_404:
	s_cmpk_lg_u32 s98, 0x100
	s_cbranch_scc1 .Lp0s_skip
	v_readlane_b32 s0, v243, 19
	v_readlane_b32 s1, v243, 61
	v_readlane_b32 s16, v243, 16
	s_cmp_eq_u32 s0, s1
	s_cbranch_scc1 .Lp0s_skip
	s_cmp_eq_u32 s0, 1
	s_cbranch_scc1 .Lp0s_ph1
	s_cmp_eq_u32 s0, 3
	s_cbranch_scc1 .Lp0s_ph3
	s_cmp_eq_u32 s0, 9
	s_cbranch_scc1 .Lp0s_ph9
	s_cmp_eq_u32 s0, 11
	s_cbranch_scc1 .Lp0s_ph11
	s_branch .Lp0s_skip
.Lp0s_ph1:
	s_cmpk_lt_u32 s16, 0x80
	s_cbranch_scc1 .Lp0s_skip
	s_cmpk_ge_u32 s16, 0xc0
	s_cbranch_scc1 .Lp0s_skip
	s_sub_i32 s69, s16, 0x80
	s_movk_i32 s100, 0x40
	s_movk_i32 s101, 639
	s_branch .Lp0s_go
.Lp0s_ph3:
	s_cmpk_lt_u32 s16, 0x40
	s_cbranch_scc1 .Lp0s_skip
	s_sub_i32 s69, s16, 0x40
	s_movk_i32 s100, 0xc0
	s_movk_i32 s101, 1759
	s_branch .Lp0s_go
.Lp0s_ph9:
	s_cmpk_lt_u32 s16, 0x80
	s_cbranch_scc1 .Lp0s_skip
	s_sub_i32 s69, s16, 0x80
	s_movk_i32 s100, 0x80
	s_movk_i32 s101, 703
	s_branch .Lp0s_go
.Lp0s_ph11:
	s_cmpk_lt_u32 s16, 0x80
	s_cbranch_scc1 .Lp0s_skip
	s_sub_i32 s69, s16, 0x80
	s_movk_i32 s100, 0x80
	s_movk_i32 s101, 479
.Lp0s_go:
	s_mov_b32 s83, s0
	v_writelane_b32 v243, s0, 61
	v_writelane_b32 v243, s2, 21
	v_writelane_b32 v243, s21, 22
	v_readlane_b32 s70, v243, 17
	v_readlane_b32 s71, v243, 18
	v_mov_b32_e32 v2, v220
	s_waitcnt vmcnt(0) lgkmcnt(0)
	s_barrier
	s_branch .Lp0_pre
